# adaLN partials of layers 1-3 deferred from prologue into P2 slack of previous layer + MOD reduction in P3; plus bias hoist
# baseline (speedup 1.0000x reference)
; #define GAS __attribute__((address_space(1)))
; __device__ __forceinline__ float silu_f(float v) { return v / (1.0f + __expf(-v)); }
; __device__ __forceinline__ void pro_a(Frame& F, CArgs a, unsigned long long& tm_acc) {
;     ...
;     {
;         GAS float* modp = (GAS float*)(ws + WS_MODP);
;         for (int it = gw; it < DEPTH * 48 * 32; it += NGW) {
;             const int ks = it & 31, cb = (it >> 5) % 48, l = it / (32 * 48);
;             const int col = cb * 256 + lane * 4, k0 = ks * 64;
;             float sv[5];
; #pragma unroll
;             for (int b = 0; b < 5; ++b) { const GAS float* cp = b < 4 ? ((const GAS float*)a->in[I_C]) + b * D : ((const GAS float*)a->in[I_CCTX]); sv[b] = silu_f(cp[k0 + lane]); }
;             f32x4 acc[5];
; #pragma unroll
;             for (int b = 0; b < 5; ++b) acc[b] = (f32x4){0.f, 0.f, 0.f, 0.f};
;             const GAS float* wp = ((const GAS float*)a->in[I_WADA]) + ((size_t)l * D + k0) * 12288 + col;
.LBB0_178:
	s_cmpk_gt_i32 s18, 0x5ff
	s_cbranch_scc1 .LBB0_183
	s_load_dwordx2 s[22:23], s[0:1], 0x8
	s_load_dwordx4 s[12:15], s[0:1], 0x18
	s_add_u32 s20, s36, 0x2a600000
	s_addc_u32 s21, s37, 0
	s_lshr_b32 s4, s19, 6
	s_waitcnt lgkmcnt(0)
	s_add_u32 s24, s22, 0x2000
	s_addc_u32 s25, s23, 0
	s_add_u32 s26, s22, 0x4000
	s_addc_u32 s27, s23, 0
	s_waitcnt vmcnt(23)
	v_mbcnt_lo_u32_b32 v2, -1, 0
	s_add_u32 s38, s22, 0x6000
	v_mbcnt_hi_u32_b32 v2, -1, v2
	s_addc_u32 s39, s23, 0
	v_lshlrev_b32_e32 v2, 2, v2
	s_add_u32 s19, s14, 0x30000
	s_waitcnt vmcnt(17)
	v_and_b32_e32 v28, 0x100, v2
	s_addc_u32 s40, s15, 0
	s_add_i32 s17, s17, s4
	s_mov_b32 s41, 0xfffd0000
	s_mov_b32 s42, 0xfffdc000
	s_mov_b32 s43, 0xfffe8000
	s_mov_b32 s44, 0xffff4000
	s_mov_b32 s45, 0xc000
	s_mov_b32 s46, 0x18000
	s_mov_b32 s47, 0x24000
	s_mov_b64 s[14:15], 0x60000
	v_mov_b32_e32 v29, 0x3c000
	s_mov_b32 s48, s18

; #define GAS __attribute__((address_space(1)))
; __device__ __forceinline__ void pro_a(Frame& F, CArgs a, unsigned long long& tm_acc) {
;     ...
; #pragma unroll 8
;             for (int kk = 0; kk < 64; ++kk) { const f32x4 w = *(const GAS f32x4*)(wp + (size_t)kk * 12288);
; #pragma unroll
;                 for (int b = 0; b < 5; ++b) acc[b] = acc[b] + w * __shfl(sv[b], kk); }
.LBB0_181:
	v_add_co_u32_e32 v26, vcc, s41, v24
	global_load_dwordx4 v[36:39], v[24:25], off
	s_nop 0
	v_addc_co_u32_e32 v27, vcc, -1, v25, vcc
	v_add_co_u32_e32 v56, vcc, s42, v24
	v_add_u32_e32 v35, s5, v28
	s_nop 0
	v_addc_co_u32_e32 v57, vcc, -1, v25, vcc
	v_add_co_u32_e32 v58, vcc, s43, v24
	ds_bpermute_b32 v68, v35, v31
	s_nop 0
	v_addc_co_u32_e32 v59, vcc, -1, v25, vcc
	v_add_co_u32_e32 v60, vcc, s44, v24
	ds_bpermute_b32 v70, v35, v32
	s_nop 0
	v_addc_co_u32_e32 v61, vcc, -1, v25, vcc
	v_add_co_u32_e32 v62, vcc, s45, v24
	global_load_dwordx4 v[40:43], v[26:27], off
	global_load_dwordx4 v[44:47], v[56:57], off
	global_load_dwordx4 v[48:51], v[58:59], off
	global_load_dwordx4 v[52:55], v[60:61], off
	v_addc_co_u32_e32 v63, vcc, 0, v25, vcc
	v_add_co_u32_e32 v64, vcc, s46, v24
	global_load_dwordx4 v[56:59], v[62:63], off
	s_nop 0
	v_addc_co_u32_e32 v65, vcc, 0, v25, vcc
	v_add_co_u32_e32 v66, vcc, s47, v24
	global_load_dwordx4 v[60:63], v[64:65], off
	s_nop 0
	v_addc_co_u32_e32 v67, vcc, 0, v25, vcc
	global_load_dwordx4 v[64:67], v[66:67], off
	ds_bpermute_b32 v26, v35, v30
	ds_bpermute_b32 v72, v35, v33
	ds_bpermute_b32 v74, v35, v34
	ds_bpermute_b32 v76, v35, v30 offset:4
	ds_bpermute_b32 v78, v35, v31 offset:4
	ds_bpermute_b32 v80, v35, v32 offset:4
	ds_bpermute_b32 v82, v35, v33 offset:4
	ds_bpermute_b32 v84, v35, v34 offset:4
	ds_bpermute_b32 v86, v35, v30 offset:8
	ds_bpermute_b32 v88, v35, v31 offset:8
	ds_bpermute_b32 v90, v35, v32 offset:8
	ds_bpermute_b32 v92, v35, v33 offset:8
	ds_bpermute_b32 v94, v35, v34 offset:8
	ds_bpermute_b32 v96, v35, v30 offset:12
	ds_bpermute_b32 v98, v35, v31 offset:12
	ds_bpermute_b32 v100, v35, v32 offset:12
	ds_bpermute_b32 v102, v35, v33 offset:12
	ds_bpermute_b32 v104, v35, v34 offset:12
	ds_bpermute_b32 v106, v35, v30 offset:16
	ds_bpermute_b32 v108, v35, v31 offset:16
	ds_bpermute_b32 v110, v35, v32 offset:16
	ds_bpermute_b32 v112, v35, v33 offset:16
	ds_bpermute_b32 v114, v35, v34 offset:16
	ds_bpermute_b32 v116, v35, v30 offset:20
	ds_bpermute_b32 v118, v35, v31 offset:20
	ds_bpermute_b32 v120, v35, v32 offset:20
	ds_bpermute_b32 v122, v35, v33 offset:20
	ds_bpermute_b32 v124, v35, v34 offset:20
	ds_bpermute_b32 v126, v35, v30 offset:24
	ds_bpermute_b32 v128, v35, v31 offset:24
	ds_bpermute_b32 v132, v35, v32 offset:24
	ds_bpermute_b32 v134, v35, v33 offset:24
	ds_bpermute_b32 v136, v35, v34 offset:24
	ds_bpermute_b32 v138, v35, v30 offset:28
	ds_bpermute_b32 v140, v35, v31 offset:28
	ds_bpermute_b32 v142, v35, v32 offset:28
	ds_bpermute_b32 v144, v35, v33 offset:28
	ds_bpermute_b32 v146, v35, v34 offset:28
	s_add_i32 s5, s5, 32
	v_lshl_add_u64 v[24:25], v[24:25], 0, s[14:15]
	s_cmpk_eq_i32 s5, 0x100
	s_waitcnt vmcnt(6) lgkmcnt(14)
	v_pk_fma_f32 v[16:17], v[42:43], v[26:27], v[16:17] op_sel_hi:[1,0,1]
	v_pk_fma_f32 v[14:15], v[40:41], v[26:27], v[14:15] op_sel_hi:[1,0,1]
	v_pk_fma_f32 v[20:21], v[42:43], v[68:69], v[20:21] op_sel_hi:[1,0,1]
	v_pk_fma_f32 v[18:19], v[40:41], v[68:69], v[18:19] op_sel_hi:[1,0,1]
	v_pk_fma_f32 v[12:13], v[42:43], v[70:71], v[12:13] op_sel_hi:[1,0,1]
	v_pk_fma_f32 v[10:11], v[40:41], v[70:71], v[10:11] op_sel_hi:[1,0,1]
	v_pk_fma_f32 v[8:9], v[42:43], v[72:73], v[8:9] op_sel_hi:[1,0,1]
	v_pk_fma_f32 v[6:7], v[40:41], v[72:73], v[6:7] op_sel_hi:[1,0,1]
	v_pk_fma_f32 v[4:5], v[42:43], v[74:75], v[4:5] op_sel_hi:[1,0,1]
	v_pk_fma_f32 v[2:3], v[40:41], v[74:75], v[2:3] op_sel_hi:[1,0,1]
	s_waitcnt vmcnt(5)
	v_pk_fma_f32 v[16:17], v[46:47], v[76:77], v[16:17] op_sel_hi:[1,0,1]
	v_pk_fma_f32 v[14:15], v[44:45], v[76:77], v[14:15] op_sel_hi:[1,0,1]
	v_pk_fma_f32 v[20:21], v[46:47], v[78:79], v[20:21] op_sel_hi:[1,0,1]
	v_pk_fma_f32 v[18:19], v[44:45], v[78:79], v[18:19] op_sel_hi:[1,0,1]
	v_pk_fma_f32 v[12:13], v[46:47], v[80:81], v[12:13] op_sel_hi:[1,0,1]
	v_pk_fma_f32 v[10:11], v[44:45], v[80:81], v[10:11] op_sel_hi:[1,0,1]
	v_pk_fma_f32 v[8:9], v[46:47], v[82:83], v[8:9] op_sel_hi:[1,0,1]
	v_pk_fma_f32 v[6:7], v[44:45], v[82:83], v[6:7] op_sel_hi:[1,0,1]
	v_pk_fma_f32 v[4:5], v[46:47], v[84:85], v[4:5] op_sel_hi:[1,0,1]
	v_pk_fma_f32 v[2:3], v[44:45], v[84:85], v[2:3] op_sel_hi:[1,0,1]
	s_waitcnt vmcnt(4)
	v_pk_fma_f32 v[16:17], v[50:51], v[86:87], v[16:17] op_sel_hi:[1,0,1]
	v_pk_fma_f32 v[14:15], v[48:49], v[86:87], v[14:15] op_sel_hi:[1,0,1]
	v_pk_fma_f32 v[20:21], v[50:51], v[88:89], v[20:21] op_sel_hi:[1,0,1]
	v_pk_fma_f32 v[18:19], v[48:49], v[88:89], v[18:19] op_sel_hi:[1,0,1]
	v_pk_fma_f32 v[12:13], v[50:51], v[90:91], v[12:13] op_sel_hi:[1,0,1]
	v_pk_fma_f32 v[10:11], v[48:49], v[90:91], v[10:11] op_sel_hi:[1,0,1]
	v_pk_fma_f32 v[8:9], v[50:51], v[92:93], v[8:9] op_sel_hi:[1,0,1]
	v_pk_fma_f32 v[6:7], v[48:49], v[92:93], v[6:7] op_sel_hi:[1,0,1]
	v_pk_fma_f32 v[4:5], v[50:51], v[94:95], v[4:5] op_sel_hi:[1,0,1]
	v_pk_fma_f32 v[2:3], v[48:49], v[94:95], v[2:3] op_sel_hi:[1,0,1]
	s_waitcnt vmcnt(3)
; #define GAS __attribute__((address_space(1)))
; __device__ __forceinline__ void pro_a(Frame& F, CArgs a, unsigned long long& tm_acc) {
;     ...
; #pragma unroll 8
;             for (int kk = 0; kk < 64; ++kk) { const f32x4 w = *(const GAS f32x4*)(wp + (size_t)kk * 12288);
; #pragma unroll
;                 for (int b = 0; b < 5; ++b) acc[b] = acc[b] + w * __shfl(sv[b], kk); }
; #pragma unroll
;             for (int b = 0; b < 5; ++b) *(GAS f32x4*)(modp + (((size_t)ks * DEPTH + l) * 5 + b) * 12288 + col) = acc[b];
;         }
	v_pk_fma_f32 v[16:17], v[54:55], v[96:97], v[16:17] op_sel_hi:[1,0,1]
	v_pk_fma_f32 v[14:15], v[52:53], v[96:97], v[14:15] op_sel_hi:[1,0,1]
	v_pk_fma_f32 v[20:21], v[54:55], v[98:99], v[20:21] op_sel_hi:[1,0,1]
	v_pk_fma_f32 v[18:19], v[52:53], v[98:99], v[18:19] op_sel_hi:[1,0,1]
	v_pk_fma_f32 v[12:13], v[54:55], v[100:101], v[12:13] op_sel_hi:[1,0,1]
	v_pk_fma_f32 v[10:11], v[52:53], v[100:101], v[10:11] op_sel_hi:[1,0,1]
	v_pk_fma_f32 v[8:9], v[54:55], v[102:103], v[8:9] op_sel_hi:[1,0,1]
	v_pk_fma_f32 v[6:7], v[52:53], v[102:103], v[6:7] op_sel_hi:[1,0,1]
	v_pk_fma_f32 v[4:5], v[54:55], v[104:105], v[4:5] op_sel_hi:[1,0,1]
	v_pk_fma_f32 v[2:3], v[52:53], v[104:105], v[2:3] op_sel_hi:[1,0,1]
	v_pk_fma_f32 v[16:17], v[38:39], v[106:107], v[16:17] op_sel_hi:[1,0,1]
	v_pk_fma_f32 v[14:15], v[36:37], v[106:107], v[14:15] op_sel_hi:[1,0,1]
	v_pk_fma_f32 v[20:21], v[38:39], v[108:109], v[20:21] op_sel_hi:[1,0,1]
	v_pk_fma_f32 v[18:19], v[36:37], v[108:109], v[18:19] op_sel_hi:[1,0,1]
	v_pk_fma_f32 v[12:13], v[38:39], v[110:111], v[12:13] op_sel_hi:[1,0,1]
	v_pk_fma_f32 v[10:11], v[36:37], v[110:111], v[10:11] op_sel_hi:[1,0,1]
	v_pk_fma_f32 v[8:9], v[38:39], v[112:113], v[8:9] op_sel_hi:[1,0,1]
	v_pk_fma_f32 v[6:7], v[36:37], v[112:113], v[6:7] op_sel_hi:[1,0,1]
	v_pk_fma_f32 v[4:5], v[38:39], v[114:115], v[4:5] op_sel_hi:[1,0,1]
	v_pk_fma_f32 v[2:3], v[36:37], v[114:115], v[2:3] op_sel_hi:[1,0,1]
	s_waitcnt vmcnt(2)
	v_pk_fma_f32 v[16:17], v[58:59], v[116:117], v[16:17] op_sel_hi:[1,0,1]
	v_pk_fma_f32 v[14:15], v[56:57], v[116:117], v[14:15] op_sel_hi:[1,0,1]
	s_waitcnt lgkmcnt(13)
	v_pk_fma_f32 v[20:21], v[58:59], v[118:119], v[20:21] op_sel_hi:[1,0,1]
	v_pk_fma_f32 v[18:19], v[56:57], v[118:119], v[18:19] op_sel_hi:[1,0,1]
	s_waitcnt lgkmcnt(12)
	v_pk_fma_f32 v[12:13], v[58:59], v[120:121], v[12:13] op_sel_hi:[1,0,1]
	v_pk_fma_f32 v[10:11], v[56:57], v[120:121], v[10:11] op_sel_hi:[1,0,1]
	s_waitcnt lgkmcnt(11)
	v_pk_fma_f32 v[8:9], v[58:59], v[122:123], v[8:9] op_sel_hi:[1,0,1]
	v_pk_fma_f32 v[6:7], v[56:57], v[122:123], v[6:7] op_sel_hi:[1,0,1]
	s_waitcnt lgkmcnt(10)
	v_pk_fma_f32 v[4:5], v[58:59], v[124:125], v[4:5] op_sel_hi:[1,0,1]
	v_pk_fma_f32 v[2:3], v[56:57], v[124:125], v[2:3] op_sel_hi:[1,0,1]
	s_waitcnt vmcnt(1) lgkmcnt(9)
	v_pk_fma_f32 v[16:17], v[62:63], v[126:127], v[16:17] op_sel_hi:[1,0,1]
	v_pk_fma_f32 v[14:15], v[60:61], v[126:127], v[14:15] op_sel_hi:[1,0,1]
	s_waitcnt lgkmcnt(8)
	v_pk_fma_f32 v[20:21], v[62:63], v[128:129], v[20:21] op_sel_hi:[1,0,1]
	v_pk_fma_f32 v[18:19], v[60:61], v[128:129], v[18:19] op_sel_hi:[1,0,1]
	s_waitcnt lgkmcnt(7)
	v_pk_fma_f32 v[12:13], v[62:63], v[132:133], v[12:13] op_sel_hi:[1,0,1]
	v_pk_fma_f32 v[10:11], v[60:61], v[132:133], v[10:11] op_sel_hi:[1,0,1]
	s_waitcnt lgkmcnt(6)
	v_pk_fma_f32 v[8:9], v[62:63], v[134:135], v[8:9] op_sel_hi:[1,0,1]
	v_pk_fma_f32 v[6:7], v[60:61], v[134:135], v[6:7] op_sel_hi:[1,0,1]
	s_waitcnt lgkmcnt(5)
	v_pk_fma_f32 v[4:5], v[62:63], v[136:137], v[4:5] op_sel_hi:[1,0,1]
	v_pk_fma_f32 v[2:3], v[60:61], v[136:137], v[2:3] op_sel_hi:[1,0,1]
	s_waitcnt vmcnt(0) lgkmcnt(4)
	v_pk_fma_f32 v[16:17], v[66:67], v[138:139], v[16:17] op_sel_hi:[1,0,1]
	v_pk_fma_f32 v[14:15], v[64:65], v[138:139], v[14:15] op_sel_hi:[1,0,1]
	s_waitcnt lgkmcnt(3)
	v_pk_fma_f32 v[20:21], v[66:67], v[140:141], v[20:21] op_sel_hi:[1,0,1]
	v_pk_fma_f32 v[18:19], v[64:65], v[140:141], v[18:19] op_sel_hi:[1,0,1]
	s_waitcnt lgkmcnt(2)
	v_pk_fma_f32 v[12:13], v[66:67], v[142:143], v[12:13] op_sel_hi:[1,0,1]
	v_pk_fma_f32 v[10:11], v[64:65], v[142:143], v[10:11] op_sel_hi:[1,0,1]
	s_waitcnt lgkmcnt(1)
	v_pk_fma_f32 v[8:9], v[66:67], v[144:145], v[8:9] op_sel_hi:[1,0,1]
	v_pk_fma_f32 v[6:7], v[64:65], v[144:145], v[6:7] op_sel_hi:[1,0,1]
	s_waitcnt lgkmcnt(0)
	v_pk_fma_f32 v[4:5], v[66:67], v[146:147], v[4:5] op_sel_hi:[1,0,1]
	v_pk_fma_f32 v[2:3], v[64:65], v[146:147], v[2:3] op_sel_hi:[1,0,1]
	s_cbranch_scc0 .LBB0_181
	s_lshl_b32 s5, s49, 2
	s_add_i32 s5, s5, s4
	v_lshl_add_u64 v[22:23], v[22:23], 2, s[20:21]
	v_mad_i64_i32 v[22:23], s[4:5], s5, v29, v[22:23]
	global_store_dwordx4 v[22:23], v[14:17], off
	s_add_i32 s48, s48, s16
	s_add_i32 s17, s17, s16
	v_add_co_u32_e32 v14, vcc, 0xc000, v22
	s_cmpk_gt_i32 s48, 0x5ff
	s_nop 0
	v_addc_co_u32_e32 v15, vcc, 0, v23, vcc
	global_store_dwordx4 v[14:15], v[18:21], off
	v_add_co_u32_e32 v14, vcc, 0x18000, v22
	s_nop 1
	v_addc_co_u32_e32 v15, vcc, 0, v23, vcc
	global_store_dwordx4 v[14:15], v[10:13], off
	s_nop 1
	v_add_co_u32_e32 v10, vcc, 0x24000, v22
	s_nop 1
	v_addc_co_u32_e32 v11, vcc, 0, v23, vcc
	global_store_dwordx4 v[10:11], v[6:9], off
	s_nop 1
	v_add_co_u32_e32 v6, vcc, 0x30000, v22
	s_nop 1
	v_addc_co_u32_e32 v7, vcc, 0, v23, vcc
	global_store_dwordx4 v[6:7], v[2:5], off
	s_cbranch_scc0 .LBB0_180

; #define GAS __attribute__((address_space(1)))
; __device__ __forceinline__ float silu_f(float v) { return v / (1.0f + __expf(-v)); }
; __device__ __forceinline__ void pro_a(Frame& F, CArgs a, unsigned long long& tm_acc) {
;     ...
;     {
;         GAS float* modp = (GAS float*)(ws + WS_MODP);
;         for (int it = gw; it < DEPTH * 48 * 32; it += NGW) {
;             const int ks = it & 31, cb = (it >> 5) % 48, l = it / (32 * 48);
;             const int col = cb * 256 + lane * 4, k0 = ks * 64;
;             float sv[5];
; #pragma unroll
;             for (int b = 0; b < 5; ++b) { const GAS float* cp = b < 4 ? ((const GAS float*)a->in[I_C]) + b * D : ((const GAS float*)a->in[I_CCTX]); sv[b] = silu_f(cp[k0 + lane]); }
;             f32x4 acc[5];
; #pragma unroll
;             for (int b = 0; b < 5; ++b) acc[b] = (f32x4){0.f, 0.f, 0.f, 0.f};
;             const GAS float* wp = ((const GAS float*)a->in[I_WADA]) + ((size_t)l * D + k0) * 12288 + col;
.LBB0_920:
	s_cmpk_lt_i32 s2, 32
	s_cbranch_scc1 .Lad_skip
	v_readlane_b32 s100, v255, 42
	s_nop 3
	s_cmp_gt_u32 s100, 2
	s_cbranch_scc1 .Lad_skip
	v_writelane_b32 v200, s4, 0
	v_writelane_b32 v200, s5, 1
	v_writelane_b32 v200, s6, 2
	v_writelane_b32 v200, s7, 3
	v_writelane_b32 v200, s8, 4
	v_writelane_b32 v200, s9, 5
	v_writelane_b32 v200, s10, 6
	v_writelane_b32 v200, s11, 7
	v_writelane_b32 v200, s12, 8
	v_writelane_b32 v200, s13, 9
	v_writelane_b32 v200, s14, 10
	v_writelane_b32 v200, s15, 11
	v_writelane_b32 v200, s16, 12
	v_writelane_b32 v200, s17, 13
	v_writelane_b32 v200, s18, 14
	v_writelane_b32 v200, s19, 15
	v_writelane_b32 v200, s20, 16
	v_writelane_b32 v200, s21, 17
	v_writelane_b32 v200, s22, 18
	v_writelane_b32 v200, s23, 19
	v_writelane_b32 v200, s24, 20
	v_writelane_b32 v200, s25, 21
	v_writelane_b32 v200, s26, 22
	v_writelane_b32 v200, s27, 23
	v_writelane_b32 v200, s28, 24
	v_writelane_b32 v200, s29, 25
	v_writelane_b32 v200, s30, 26
	v_writelane_b32 v200, s31, 27
	v_writelane_b32 v200, s32, 28
	v_writelane_b32 v200, s33, 29
	v_writelane_b32 v200, s34, 30
	v_writelane_b32 v200, s35, 31
	v_writelane_b32 v200, s36, 32
	v_writelane_b32 v200, s37, 33
	v_writelane_b32 v200, s38, 34
	v_writelane_b32 v200, s39, 35
	v_writelane_b32 v200, s40, 36
	v_writelane_b32 v200, s41, 37
	v_writelane_b32 v200, s42, 38
	v_writelane_b32 v200, s43, 39
	v_writelane_b32 v200, s44, 40
	v_writelane_b32 v200, s45, 41
	v_writelane_b32 v200, s46, 42
	v_writelane_b32 v200, s47, 43
	v_writelane_b32 v200, s48, 44
	v_writelane_b32 v200, s49, 45
	v_writelane_b32 v200, s50, 46
	v_writelane_b32 v200, s51, 47
	v_writelane_b32 v200, s52, 48
	v_writelane_b32 v200, s53, 49
	s_load_dwordx2 s[36:37], s[0:1], 0x130
	v_readfirstlane_b32 s19, v0
	v_and_b32_e32 v130, 63, v0
	s_lshr_b32 s4, s19, 6
	s_lshl_b32 s17, s2, 3
	s_addk_i32 s17, 0xff00
	s_add_i32 s5, s100, 1
	s_mulk_i32 s5, 0x600
	s_add_i32 s17, s17, s5
	s_add_i32 s18, s17, s4
	s_add_i32 s101, s5, 0x5ff
	s_movk_i32 s16, 0x700
	v_lshlrev_b32_e32 v130, 2, v130
	s_waitcnt lgkmcnt(0)
	s_cmp_gt_i32 s18, s101
	s_cbranch_scc1 .Lad_exit
	s_load_dwordx2 s[22:23], s[0:1], 0x8
	s_load_dwordx4 s[12:15], s[0:1], 0x18
	s_add_u32 s20, s36, 0x46000000
	s_addc_u32 s21, s37, 0
	s_lshr_b32 s4, s19, 6
	s_waitcnt lgkmcnt(0)
	s_add_u32 s24, s22, 0x2000
	s_addc_u32 s25, s23, 0
	s_add_u32 s26, s22, 0x4000
	s_addc_u32 s27, s23, 0
	s_waitcnt vmcnt(23)
	v_mbcnt_lo_u32_b32 v2, -1, 0
	s_add_u32 s38, s22, 0x6000
	v_mbcnt_hi_u32_b32 v2, -1, v2
	s_addc_u32 s39, s23, 0
	v_lshlrev_b32_e32 v2, 2, v2
	s_add_u32 s19, s14, 0x30000
	s_waitcnt vmcnt(17)
	v_and_b32_e32 v28, 0x100, v2
	s_addc_u32 s40, s15, 0
	s_add_i32 s17, s17, s4
	s_mov_b32 s41, 0xfffd0000
	s_mov_b32 s42, 0xfffdc000
	s_mov_b32 s43, 0xfffe8000
	s_mov_b32 s44, 0xffff4000
	s_mov_b32 s45, 0xc000
	s_mov_b32 s46, 0x18000
	s_mov_b32 s47, 0x24000
	s_mov_b64 s[14:15], 0x60000
	v_mov_b32_e32 v29, 0x3c000
	s_mov_b32 s48, s18

; #define GAS __attribute__((address_space(1)))
; __device__ __forceinline__ void pro_a(Frame& F, CArgs a, unsigned long long& tm_acc) {
;     ...
; #pragma unroll 8
;             for (int kk = 0; kk < 64; ++kk) { const f32x4 w = *(const GAS f32x4*)(wp + (size_t)kk * 12288);
; #pragma unroll
;                 for (int b = 0; b < 5; ++b) acc[b] = acc[b] + w * __shfl(sv[b], kk); }
.Lad_181:
	v_add_co_u32_e32 v26, vcc, s41, v24
	global_load_dwordx4 v[36:39], v[24:25], off
	s_nop 0
	v_addc_co_u32_e32 v27, vcc, -1, v25, vcc
	v_add_co_u32_e32 v56, vcc, s42, v24
	v_add_u32_e32 v35, s5, v28
	s_nop 0
	v_addc_co_u32_e32 v57, vcc, -1, v25, vcc
	v_add_co_u32_e32 v58, vcc, s43, v24
	ds_bpermute_b32 v68, v35, v31
	s_nop 0
	v_addc_co_u32_e32 v59, vcc, -1, v25, vcc
	v_add_co_u32_e32 v60, vcc, s44, v24
	ds_bpermute_b32 v70, v35, v32
	s_nop 0
	v_addc_co_u32_e32 v61, vcc, -1, v25, vcc
	v_add_co_u32_e32 v62, vcc, s45, v24
	global_load_dwordx4 v[40:43], v[26:27], off
	global_load_dwordx4 v[44:47], v[56:57], off
	global_load_dwordx4 v[48:51], v[58:59], off
	global_load_dwordx4 v[52:55], v[60:61], off
	v_addc_co_u32_e32 v63, vcc, 0, v25, vcc
	v_add_co_u32_e32 v64, vcc, s46, v24
	global_load_dwordx4 v[56:59], v[62:63], off
	s_nop 0
	v_addc_co_u32_e32 v65, vcc, 0, v25, vcc
	v_add_co_u32_e32 v66, vcc, s47, v24
	global_load_dwordx4 v[60:63], v[64:65], off
	s_nop 0
	v_addc_co_u32_e32 v67, vcc, 0, v25, vcc
	global_load_dwordx4 v[64:67], v[66:67], off
	ds_bpermute_b32 v26, v35, v30
	ds_bpermute_b32 v72, v35, v33
	ds_bpermute_b32 v74, v35, v34
	ds_bpermute_b32 v76, v35, v30 offset:4
	ds_bpermute_b32 v78, v35, v31 offset:4
	ds_bpermute_b32 v80, v35, v32 offset:4
	ds_bpermute_b32 v82, v35, v33 offset:4
	ds_bpermute_b32 v84, v35, v34 offset:4
	ds_bpermute_b32 v86, v35, v30 offset:8
	ds_bpermute_b32 v88, v35, v31 offset:8
	ds_bpermute_b32 v90, v35, v32 offset:8
	ds_bpermute_b32 v92, v35, v33 offset:8
	ds_bpermute_b32 v94, v35, v34 offset:8
	ds_bpermute_b32 v96, v35, v30 offset:12
	ds_bpermute_b32 v98, v35, v31 offset:12
	ds_bpermute_b32 v100, v35, v32 offset:12
	ds_bpermute_b32 v102, v35, v33 offset:12
	ds_bpermute_b32 v104, v35, v34 offset:12
	ds_bpermute_b32 v106, v35, v30 offset:16
	ds_bpermute_b32 v108, v35, v31 offset:16
	ds_bpermute_b32 v110, v35, v32 offset:16
	ds_bpermute_b32 v112, v35, v33 offset:16
	ds_bpermute_b32 v114, v35, v34 offset:16
	ds_bpermute_b32 v116, v35, v30 offset:20
	ds_bpermute_b32 v118, v35, v31 offset:20
	ds_bpermute_b32 v120, v35, v32 offset:20
	ds_bpermute_b32 v122, v35, v33 offset:20
	ds_bpermute_b32 v124, v35, v34 offset:20
	ds_bpermute_b32 v126, v35, v30 offset:24
	ds_bpermute_b32 v128, v35, v31 offset:24
	ds_bpermute_b32 v132, v35, v32 offset:24
	ds_bpermute_b32 v134, v35, v33 offset:24
	ds_bpermute_b32 v136, v35, v34 offset:24
	ds_bpermute_b32 v138, v35, v30 offset:28
	ds_bpermute_b32 v140, v35, v31 offset:28
	ds_bpermute_b32 v142, v35, v32 offset:28
	ds_bpermute_b32 v144, v35, v33 offset:28
	ds_bpermute_b32 v146, v35, v34 offset:28
	s_add_i32 s5, s5, 32
	v_lshl_add_u64 v[24:25], v[24:25], 0, s[14:15]
	s_cmpk_eq_i32 s5, 0x100
	s_waitcnt vmcnt(6) lgkmcnt(14)
	v_pk_fma_f32 v[16:17], v[42:43], v[26:27], v[16:17] op_sel_hi:[1,0,1]
	v_pk_fma_f32 v[14:15], v[40:41], v[26:27], v[14:15] op_sel_hi:[1,0,1]
	v_pk_fma_f32 v[20:21], v[42:43], v[68:69], v[20:21] op_sel_hi:[1,0,1]
	v_pk_fma_f32 v[18:19], v[40:41], v[68:69], v[18:19] op_sel_hi:[1,0,1]
	v_pk_fma_f32 v[12:13], v[42:43], v[70:71], v[12:13] op_sel_hi:[1,0,1]
	v_pk_fma_f32 v[10:11], v[40:41], v[70:71], v[10:11] op_sel_hi:[1,0,1]
	v_pk_fma_f32 v[8:9], v[42:43], v[72:73], v[8:9] op_sel_hi:[1,0,1]
	v_pk_fma_f32 v[6:7], v[40:41], v[72:73], v[6:7] op_sel_hi:[1,0,1]
	v_pk_fma_f32 v[4:5], v[42:43], v[74:75], v[4:5] op_sel_hi:[1,0,1]
	v_pk_fma_f32 v[2:3], v[40:41], v[74:75], v[2:3] op_sel_hi:[1,0,1]
	s_waitcnt vmcnt(5)
	v_pk_fma_f32 v[16:17], v[46:47], v[76:77], v[16:17] op_sel_hi:[1,0,1]
	v_pk_fma_f32 v[14:15], v[44:45], v[76:77], v[14:15] op_sel_hi:[1,0,1]
	v_pk_fma_f32 v[20:21], v[46:47], v[78:79], v[20:21] op_sel_hi:[1,0,1]
	v_pk_fma_f32 v[18:19], v[44:45], v[78:79], v[18:19] op_sel_hi:[1,0,1]
	v_pk_fma_f32 v[12:13], v[46:47], v[80:81], v[12:13] op_sel_hi:[1,0,1]
	v_pk_fma_f32 v[10:11], v[44:45], v[80:81], v[10:11] op_sel_hi:[1,0,1]
	v_pk_fma_f32 v[8:9], v[46:47], v[82:83], v[8:9] op_sel_hi:[1,0,1]
	v_pk_fma_f32 v[6:7], v[44:45], v[82:83], v[6:7] op_sel_hi:[1,0,1]
	v_pk_fma_f32 v[4:5], v[46:47], v[84:85], v[4:5] op_sel_hi:[1,0,1]
	v_pk_fma_f32 v[2:3], v[44:45], v[84:85], v[2:3] op_sel_hi:[1,0,1]
	s_waitcnt vmcnt(4)
	v_pk_fma_f32 v[16:17], v[50:51], v[86:87], v[16:17] op_sel_hi:[1,0,1]
	v_pk_fma_f32 v[14:15], v[48:49], v[86:87], v[14:15] op_sel_hi:[1,0,1]
	v_pk_fma_f32 v[20:21], v[50:51], v[88:89], v[20:21] op_sel_hi:[1,0,1]
	v_pk_fma_f32 v[18:19], v[48:49], v[88:89], v[18:19] op_sel_hi:[1,0,1]
	v_pk_fma_f32 v[12:13], v[50:51], v[90:91], v[12:13] op_sel_hi:[1,0,1]
	v_pk_fma_f32 v[10:11], v[48:49], v[90:91], v[10:11] op_sel_hi:[1,0,1]
	v_pk_fma_f32 v[8:9], v[50:51], v[92:93], v[8:9] op_sel_hi:[1,0,1]
	v_pk_fma_f32 v[6:7], v[48:49], v[92:93], v[6:7] op_sel_hi:[1,0,1]
	v_pk_fma_f32 v[4:5], v[50:51], v[94:95], v[4:5] op_sel_hi:[1,0,1]
	v_pk_fma_f32 v[2:3], v[48:49], v[94:95], v[2:3] op_sel_hi:[1,0,1]
	s_waitcnt vmcnt(3)
; #define GAS __attribute__((address_space(1)))
; __device__ __forceinline__ void pro_a(Frame& F, CArgs a, unsigned long long& tm_acc) {
;     ...
; #pragma unroll 8
;             for (int kk = 0; kk < 64; ++kk) { const f32x4 w = *(const GAS f32x4*)(wp + (size_t)kk * 12288);
; #pragma unroll
;                 for (int b = 0; b < 5; ++b) acc[b] = acc[b] + w * __shfl(sv[b], kk); }
; #pragma unroll
;             for (int b = 0; b < 5; ++b) *(GAS f32x4*)(modp + (((size_t)ks * DEPTH + l) * 5 + b) * 12288 + col) = acc[b];
;         }
	v_pk_fma_f32 v[16:17], v[54:55], v[96:97], v[16:17] op_sel_hi:[1,0,1]
	v_pk_fma_f32 v[14:15], v[52:53], v[96:97], v[14:15] op_sel_hi:[1,0,1]
	v_pk_fma_f32 v[20:21], v[54:55], v[98:99], v[20:21] op_sel_hi:[1,0,1]
	v_pk_fma_f32 v[18:19], v[52:53], v[98:99], v[18:19] op_sel_hi:[1,0,1]
	v_pk_fma_f32 v[12:13], v[54:55], v[100:101], v[12:13] op_sel_hi:[1,0,1]
	v_pk_fma_f32 v[10:11], v[52:53], v[100:101], v[10:11] op_sel_hi:[1,0,1]
	v_pk_fma_f32 v[8:9], v[54:55], v[102:103], v[8:9] op_sel_hi:[1,0,1]
	v_pk_fma_f32 v[6:7], v[52:53], v[102:103], v[6:7] op_sel_hi:[1,0,1]
	v_pk_fma_f32 v[4:5], v[54:55], v[104:105], v[4:5] op_sel_hi:[1,0,1]
	v_pk_fma_f32 v[2:3], v[52:53], v[104:105], v[2:3] op_sel_hi:[1,0,1]
	v_pk_fma_f32 v[16:17], v[38:39], v[106:107], v[16:17] op_sel_hi:[1,0,1]
	v_pk_fma_f32 v[14:15], v[36:37], v[106:107], v[14:15] op_sel_hi:[1,0,1]
	v_pk_fma_f32 v[20:21], v[38:39], v[108:109], v[20:21] op_sel_hi:[1,0,1]
	v_pk_fma_f32 v[18:19], v[36:37], v[108:109], v[18:19] op_sel_hi:[1,0,1]
	v_pk_fma_f32 v[12:13], v[38:39], v[110:111], v[12:13] op_sel_hi:[1,0,1]
	v_pk_fma_f32 v[10:11], v[36:37], v[110:111], v[10:11] op_sel_hi:[1,0,1]
	v_pk_fma_f32 v[8:9], v[38:39], v[112:113], v[8:9] op_sel_hi:[1,0,1]
	v_pk_fma_f32 v[6:7], v[36:37], v[112:113], v[6:7] op_sel_hi:[1,0,1]
	v_pk_fma_f32 v[4:5], v[38:39], v[114:115], v[4:5] op_sel_hi:[1,0,1]
	v_pk_fma_f32 v[2:3], v[36:37], v[114:115], v[2:3] op_sel_hi:[1,0,1]
	s_waitcnt vmcnt(2)
	v_pk_fma_f32 v[16:17], v[58:59], v[116:117], v[16:17] op_sel_hi:[1,0,1]
	v_pk_fma_f32 v[14:15], v[56:57], v[116:117], v[14:15] op_sel_hi:[1,0,1]
	s_waitcnt lgkmcnt(13)
	v_pk_fma_f32 v[20:21], v[58:59], v[118:119], v[20:21] op_sel_hi:[1,0,1]
	v_pk_fma_f32 v[18:19], v[56:57], v[118:119], v[18:19] op_sel_hi:[1,0,1]
	s_waitcnt lgkmcnt(12)
	v_pk_fma_f32 v[12:13], v[58:59], v[120:121], v[12:13] op_sel_hi:[1,0,1]
	v_pk_fma_f32 v[10:11], v[56:57], v[120:121], v[10:11] op_sel_hi:[1,0,1]
	s_waitcnt lgkmcnt(11)
	v_pk_fma_f32 v[8:9], v[58:59], v[122:123], v[8:9] op_sel_hi:[1,0,1]
	v_pk_fma_f32 v[6:7], v[56:57], v[122:123], v[6:7] op_sel_hi:[1,0,1]
	s_waitcnt lgkmcnt(10)
	v_pk_fma_f32 v[4:5], v[58:59], v[124:125], v[4:5] op_sel_hi:[1,0,1]
	v_pk_fma_f32 v[2:3], v[56:57], v[124:125], v[2:3] op_sel_hi:[1,0,1]
	s_waitcnt vmcnt(1) lgkmcnt(9)
	v_pk_fma_f32 v[16:17], v[62:63], v[126:127], v[16:17] op_sel_hi:[1,0,1]
	v_pk_fma_f32 v[14:15], v[60:61], v[126:127], v[14:15] op_sel_hi:[1,0,1]
	s_waitcnt lgkmcnt(8)
	v_pk_fma_f32 v[20:21], v[62:63], v[128:129], v[20:21] op_sel_hi:[1,0,1]
	v_pk_fma_f32 v[18:19], v[60:61], v[128:129], v[18:19] op_sel_hi:[1,0,1]
	s_waitcnt lgkmcnt(7)
	v_pk_fma_f32 v[12:13], v[62:63], v[132:133], v[12:13] op_sel_hi:[1,0,1]
	v_pk_fma_f32 v[10:11], v[60:61], v[132:133], v[10:11] op_sel_hi:[1,0,1]
	s_waitcnt lgkmcnt(6)
	v_pk_fma_f32 v[8:9], v[62:63], v[134:135], v[8:9] op_sel_hi:[1,0,1]
	v_pk_fma_f32 v[6:7], v[60:61], v[134:135], v[6:7] op_sel_hi:[1,0,1]
	s_waitcnt lgkmcnt(5)
	v_pk_fma_f32 v[4:5], v[62:63], v[136:137], v[4:5] op_sel_hi:[1,0,1]
	v_pk_fma_f32 v[2:3], v[60:61], v[136:137], v[2:3] op_sel_hi:[1,0,1]
	s_waitcnt vmcnt(0) lgkmcnt(4)
	v_pk_fma_f32 v[16:17], v[66:67], v[138:139], v[16:17] op_sel_hi:[1,0,1]
	v_pk_fma_f32 v[14:15], v[64:65], v[138:139], v[14:15] op_sel_hi:[1,0,1]
	s_waitcnt lgkmcnt(3)
	v_pk_fma_f32 v[20:21], v[66:67], v[140:141], v[20:21] op_sel_hi:[1,0,1]
	v_pk_fma_f32 v[18:19], v[64:65], v[140:141], v[18:19] op_sel_hi:[1,0,1]
	s_waitcnt lgkmcnt(2)
	v_pk_fma_f32 v[12:13], v[66:67], v[142:143], v[12:13] op_sel_hi:[1,0,1]
	v_pk_fma_f32 v[10:11], v[64:65], v[142:143], v[10:11] op_sel_hi:[1,0,1]
	s_waitcnt lgkmcnt(1)
	v_pk_fma_f32 v[8:9], v[66:67], v[144:145], v[8:9] op_sel_hi:[1,0,1]
	v_pk_fma_f32 v[6:7], v[64:65], v[144:145], v[6:7] op_sel_hi:[1,0,1]
	s_waitcnt lgkmcnt(0)
	v_pk_fma_f32 v[4:5], v[66:67], v[146:147], v[4:5] op_sel_hi:[1,0,1]
	v_pk_fma_f32 v[2:3], v[64:65], v[146:147], v[2:3] op_sel_hi:[1,0,1]
	s_cbranch_scc0 .Lad_181
	s_lshl_b32 s5, s49, 2
	s_add_i32 s5, s5, s4
	v_lshl_add_u64 v[22:23], v[22:23], 2, s[20:21]
	v_mad_i64_i32 v[22:23], s[4:5], s5, v29, v[22:23]
	global_store_dwordx4 v[22:23], v[14:17], off
	s_add_i32 s48, s48, s16
	s_add_i32 s17, s17, s16
	v_add_co_u32_e32 v14, vcc, 0xc000, v22
	s_cmp_gt_i32 s48, s101
	s_nop 0
	v_addc_co_u32_e32 v15, vcc, 0, v23, vcc
	global_store_dwordx4 v[14:15], v[18:21], off
	v_add_co_u32_e32 v14, vcc, 0x18000, v22
	s_nop 1
	v_addc_co_u32_e32 v15, vcc, 0, v23, vcc
	global_store_dwordx4 v[14:15], v[10:13], off
	s_nop 1
	v_add_co_u32_e32 v10, vcc, 0x24000, v22
	s_nop 1
	v_addc_co_u32_e32 v11, vcc, 0, v23, vcc
	global_store_dwordx4 v[10:11], v[6:9], off
	s_nop 1
	v_add_co_u32_e32 v6, vcc, 0x30000, v22
	s_nop 1
	v_addc_co_u32_e32 v7, vcc, 0, v23, vcc
	global_store_dwordx4 v[6:7], v[2:5], off
	s_cbranch_scc0 .Lad_180
.Lad_exit:
	s_nop 0
	v_readlane_b32 s4, v200, 0
	v_readlane_b32 s5, v200, 1
	v_readlane_b32 s6, v200, 2
	v_readlane_b32 s7, v200, 3
	v_readlane_b32 s8, v200, 4
	v_readlane_b32 s9, v200, 5
	v_readlane_b32 s10, v200, 6
	v_readlane_b32 s11, v200, 7
	v_readlane_b32 s12, v200, 8
	v_readlane_b32 s13, v200, 9
	v_readlane_b32 s14, v200, 10
	v_readlane_b32 s15, v200, 11
	v_readlane_b32 s16, v200, 12
	v_readlane_b32 s17, v200, 13
	v_readlane_b32 s18, v200, 14
	v_readlane_b32 s19, v200, 15
	v_readlane_b32 s20, v200, 16
	v_readlane_b32 s21, v200, 17
	v_readlane_b32 s22, v200, 18
	v_readlane_b32 s23, v200, 19
	v_readlane_b32 s24, v200, 20
	v_readlane_b32 s25, v200, 21
	v_readlane_b32 s26, v200, 22
	v_readlane_b32 s27, v200, 23
	v_readlane_b32 s28, v200, 24
	v_readlane_b32 s29, v200, 25
	v_readlane_b32 s30, v200, 26
	v_readlane_b32 s31, v200, 27
	v_readlane_b32 s32, v200, 28
	v_readlane_b32 s33, v200, 29
	v_readlane_b32 s34, v200, 30
	v_readlane_b32 s35, v200, 31
	v_readlane_b32 s36, v200, 32
	v_readlane_b32 s37, v200, 33
	v_readlane_b32 s38, v200, 34
	v_readlane_b32 s39, v200, 35
	v_readlane_b32 s40, v200, 36
	v_readlane_b32 s41, v200, 37
	v_readlane_b32 s42, v200, 38
	v_readlane_b32 s43, v200, 39
	v_readlane_b32 s44, v200, 40
	v_readlane_b32 s45, v200, 41
	v_readlane_b32 s46, v200, 42
	v_readlane_b32 s47, v200, 43
	v_readlane_b32 s48, v200, 44
	v_readlane_b32 s49, v200, 45
	v_readlane_b32 s50, v200, 46
	v_readlane_b32 s51, v200, 47
	v_readlane_b32 s52, v200, 48
	v_readlane_b32 s53, v200, 49
	s_nop 3

; #define GAS __attribute__((address_space(1)))
; __device__ __forceinline__ void pro_b(Frame& F, CArgs a) {
;     const GAS float* modp = (const GAS float*)(F.ws + WS_MODP); GAS float* mod = (GAS float*)(F.ws + WS_MOD);
;     for (int e = F.blk * 512 + F.tid; e < DEPTH * 5 * 12288; e += F.G * 512) {
;         const int j = e % 12288, l = e / (5 * 12288);
;         float s = ((const GAS float*)a->in[I_BADA])[l * 12288 + j];
; #pragma unroll 8
;         for (int ks = 0; ks < 32; ++ks) s += modp[(size_t)ks * DEPTH * 5 * 12288 + e];
;         mod[e] = s;
;     }
.LBB0_1056:
	v_readlane_b32 s100, v255, 42
	s_nop 3
	s_cmp_gt_u32 s100, 2
	s_cbranch_scc1 .Lmr_skip
	v_writelane_b32 v200, s4, 0
	v_writelane_b32 v200, s5, 1
	v_writelane_b32 v200, s6, 2
	v_writelane_b32 v200, s7, 3
	v_writelane_b32 v200, s8, 4
	v_writelane_b32 v200, s9, 5
	v_writelane_b32 v200, s10, 6
	v_writelane_b32 v200, s11, 7
	v_writelane_b32 v200, s12, 8
	v_writelane_b32 v200, s13, 9
	v_writelane_b32 v200, s14, 10
	v_writelane_b32 v200, s15, 11
	v_writelane_b32 v200, s16, 12
	v_writelane_b32 v200, s17, 13
	v_writelane_b32 v200, s18, 14
	v_writelane_b32 v200, s19, 15
	v_writelane_b32 v200, s20, 16
	v_writelane_b32 v200, s21, 17
	v_writelane_b32 v200, s22, 18
	v_writelane_b32 v200, s23, 19
	s_add_i32 s100, s100, 1
	s_mul_i32 s100, s100, 0xf000
	s_add_i32 s101, s100, 0xf000
	s_mov_b32 s4, s101
	v_lshl_add_u32 v2, s2, 9, v0
	v_add_u32_e32 v2, s100, v2
	s_load_dwordx2 s[14:15], s[0:1], 0x130
	v_cmp_gt_i32_e32 vcc, s4, v2
	s_waitcnt lgkmcnt(0)
	s_and_saveexec_b64 s[4:5], vcc
	s_cbranch_execz .Lmr_331
	s_load_dwordx2 s[12:13], s[0:1], 0x28
	s_lshl_b32 s8, s3, 9
	s_add_u32 s10, s14, 0x100000
	s_addc_u32 s11, s15, 0
	v_ashrrev_i32_e32 v3, 31, v2
	s_ashr_i32 s9, s8, 31
	v_lshl_add_u64 v[4:5], v[2:3], 2, s[14:15]
	s_lshl_b64 s[14:15], s[8:9], 2
	s_mov_b64 s[16:17], 0
	s_mov_b32 s9, 0x2aaaaaab
	s_movk_i32 s20, 0x3000
	s_mov_b32 s21, 0x88888889
	s_add_i32 s22, s101, -1

; #define GAS __attribute__((address_space(1)))
; __device__ __forceinline__ void pro_b(Frame& F, CArgs a) {
;     ...
;     for (int e = F.blk * 512 + F.tid; e < DEPTH * 5 * 12288; e += F.G * 512) {
;         const int j = e % 12288, l = e / (5 * 12288);
;         float s = ((const GAS float*)a->in[I_BADA])[l * 12288 + j];
; #pragma unroll 8
;         for (int ks = 0; ks < 32; ++ks) s += modp[(size_t)ks * DEPTH * 5 * 12288 + e];
;         mod[e] = s;
;     }
.Lmr_329:
	v_lshl_add_u64 v[6:7], v[4:5], 0, s[18:19]
	v_add_co_u32_e32 v8, vcc, 0x46000000, v6
	s_add_u32 s18, s18, 0x780000
	s_nop 0
	v_addc_co_u32_e32 v9, vcc, 0, v7, vcc
	s_waitcnt vmcnt(22)
	v_add_co_u32_e32 v10, vcc, 0x460f0000, v6
	s_addc_u32 s19, s19, 0
	s_nop 0
	v_addc_co_u32_e32 v11, vcc, 0, v7, vcc
	v_add_co_u32_e32 v12, vcc, 0x461e0000, v6
	global_load_dword v3, v[8:9], off
	global_load_dword v14, v[10:11], off
	v_addc_co_u32_e32 v13, vcc, 0, v7, vcc
	v_add_co_u32_e32 v8, vcc, 0x462d0000, v6
	s_cmp_eq_u32 s18, 0x1e00000
	s_nop 0
	v_addc_co_u32_e32 v9, vcc, 0, v7, vcc
	v_add_co_u32_e32 v10, vcc, 0x463c0000, v6
	global_load_dword v15, v[12:13], off
	global_load_dword v16, v[8:9], off
	v_addc_co_u32_e32 v11, vcc, 0, v7, vcc
	v_add_co_u32_e32 v8, vcc, 0x464b0000, v6
	s_waitcnt vmcnt(3)
	v_add_f32_e32 v1, v1, v3
	v_addc_co_u32_e32 v9, vcc, 0, v7, vcc
	v_add_co_u32_e32 v12, vcc, 0x465a0000, v6
	global_load_dword v17, v[10:11], off
	global_load_dword v18, v[8:9], off
	v_addc_co_u32_e32 v13, vcc, 0, v7, vcc
	v_add_co_u32_e32 v6, vcc, 0x46690000, v6
	s_waitcnt vmcnt(4)
	v_add_f32_e32 v1, v1, v14
	v_addc_co_u32_e32 v7, vcc, 0, v7, vcc
	global_load_dword v8, v[12:13], off
	global_load_dword v9, v[6:7], off
	s_waitcnt vmcnt(5)
	v_add_f32_e32 v1, v1, v15
	s_waitcnt vmcnt(4)
	v_add_f32_e32 v1, v1, v16
	s_waitcnt vmcnt(3)
	v_add_f32_e32 v1, v1, v17
	s_waitcnt vmcnt(2)
	v_add_f32_e32 v1, v1, v18
	s_waitcnt vmcnt(1)
	v_add_f32_e32 v1, v1, v8
	s_waitcnt vmcnt(0)
	v_add_f32_e32 v1, v1, v9
	s_cbranch_scc0 .Lmr_329
	v_ashrrev_i32_e32 v3, 31, v2
	v_lshl_add_u64 v[6:7], v[2:3], 2, s[10:11]
	v_add_u32_e32 v2, s8, v2
	v_cmp_lt_i32_e32 vcc, s22, v2
	s_or_b64 s[16:17], vcc, s[16:17]
	v_lshl_add_u64 v[4:5], v[4:5], 0, s[14:15]
	global_store_dword v[6:7], v1, off
	s_andn2_b64 exec, exec, s[16:17]
	s_cbranch_execnz .Lmr_328
.Lmr_331:
	s_or_b64 exec, exec, s[4:5]
	s_nop 0
	v_readlane_b32 s4, v200, 0
	v_readlane_b32 s5, v200, 1
	v_readlane_b32 s6, v200, 2
	v_readlane_b32 s7, v200, 3
	v_readlane_b32 s8, v200, 4
	v_readlane_b32 s9, v200, 5
	v_readlane_b32 s10, v200, 6
	v_readlane_b32 s11, v200, 7
	v_readlane_b32 s12, v200, 8
	v_readlane_b32 s13, v200, 9
	v_readlane_b32 s14, v200, 10
	v_readlane_b32 s15, v200, 11
	v_readlane_b32 s16, v200, 12
	v_readlane_b32 s17, v200, 13
	v_readlane_b32 s18, v200, 14
	v_readlane_b32 s19, v200, 15
	v_readlane_b32 s20, v200, 16
	v_readlane_b32 s21, v200, 17
	v_readlane_b32 s22, v200, 18
	v_readlane_b32 s23, v200, 19
	s_nop 3
